# NSA sliding window: interior tiles take a QK block without per-element window/causal mask arithmetic (mask provably all-true there)
# speedup vs baseline: 1.0132x; 1.0132x over previous
; __device__ __forceinline__ void phase_nsa_attn(const Params& p, char* smem, volatile LAS unsigned* vb_) {
;     ...
;       for (int i = 0; i < ntile; ++i) {
;         const int k0 = lo + i * 64;
;         const int kx = lo + (i + 1 < ntile ? i + 1 : i) * 64;
;         f32x4 st[4];
;         qk64(kA, qf, scale, [&](int ko) { const int ks = k0 + ko; return (ks <= s) && (ks + 512 > s); }, lane, st);
.LBB0_103:
	v_readfirstlane_b32 s98, v93
	s_cmp_eq_u32 s11, 0
	s_cbranch_scc1 .Lnw_slow
	s_cmp_lt_i32 s11, s98
	s_cbranch_scc1 .Lnw_fast

; #define EXP2F(x) __builtin_amdgcn_exp2f(x)
; #define SB0 __builtin_amdgcn_sched_barrier(0)
; __device__ __forceinline__ void softmax_update(f32x4 (&st)[4], float& m, float& lsum, f32x4 (&o)[4]) {
;   float mx = -1e30f;
; #pragma unroll
;   for (int kt = 0; kt < 4; ++kt)
; #pragma unroll
;     for (int r = 0; r < 4; ++r) mx = fmaxf(mx, st[kt][r]);
;   mx = fmaxf(mx, __shfl_xor(mx, 16));
;   mx = fmaxf(mx, __shfl_xor(mx, 32));
;   const float mnew = fmaxf(m, mx);
;   const float alpha = EXP2F(m - mnew);
;   float ps = 0.f;
; #pragma unroll
;   for (int kt = 0; kt < 4; ++kt)
; #pragma unroll
;     for (int r = 0; r < 4; ++r) {
;       const float pv = EXP2F(st[kt][r] - mnew);
;       st[kt][r] = pv;
;       ps += pv;
;     }
;   lsum = lsum * alpha + ps;
;   m = mnew;
;   if (__builtin_amdgcn_ballot_w64(alpha != 1.0f)) {
; #pragma unroll
;     for (int dt = 0; dt < 4; ++dt) o[dt] *= alpha;
;   }
; __device__ __forceinline__ void phase_nsa_attn(const Params& p, char* smem, volatile LAS unsigned* vb_) {
;     ...
;       for (int i = 0; i < ntile; ++i) {
;         const int k0 = lo + i * 64;
;         const int kx = lo + (i + 1 < ntile ? i + 1 : i) * 64;
;         f32x4 st[4];
;         qk64(kA, qf, scale, [&](int ko) { const int ks = k0 + ko; return (ks <= s) && (ks + 512 > s); }, lane, st);
;         SB0;
;         k_load64(kA, Kw + (size_t)kx * 64, lane);
;         SB0;
;         softmax_update(st, m, lsum, o);
.Lnw_fast:
	s_waitcnt vmcnt(15)
	v_mfma_f32_16x16x32_bf16 v[88:91], v[88:91], v[4:7], 0
	s_add_i32 s22, s11, 1
	v_cmp_lt_i32_e32 vcc, s11, v93
	v_mov_b32_e32 v2, s11
	v_mov_b32_e32 v3, s22
	s_waitcnt vmcnt(14)
	v_mfma_f32_16x16x32_bf16 v[84:87], v[84:87], v[8:11], v[88:91]
	v_cndmask_b32_e32 v2, v2, v3, vcc
	s_waitcnt vmcnt(13)
	v_mfma_f32_16x16x32_bf16 v[80:83], v[80:83], v[4:7], 0
	s_waitcnt vmcnt(12)
	v_mfma_f32_16x16x32_bf16 v[76:79], v[76:79], v[8:11], v[80:83]
	s_waitcnt vmcnt(11)
	v_mfma_f32_16x16x32_bf16 v[72:75], v[72:75], v[4:7], 0
	s_waitcnt vmcnt(10)
	v_mfma_f32_16x16x32_bf16 v[68:71], v[68:71], v[8:11], v[72:75]
	s_waitcnt vmcnt(9)
	v_mfma_f32_16x16x32_bf16 v[52:55], v[52:55], v[4:7], 0
	s_waitcnt vmcnt(8)
	v_mfma_f32_16x16x32_bf16 v[44:47], v[44:47], v[8:11], v[52:55]
	v_mov_b32_e32 v92, v98
	v_lshl_add_u32 v2, v2, 6, v0
	v_mul_f32_e32 v99, 0x3e38aa3b, v84
	v_mul_f32_e32 v100, 0x3e38aa3b, v85
	v_mul_f32_e32 v101, 0x3e38aa3b, v86
	v_mul_f32_e32 v102, 0x3e38aa3b, v87
	v_mul_f32_e32 v103, 0x3e38aa3b, v76
	v_mul_f32_e32 v104, 0x3e38aa3b, v77
	v_mul_f32_e32 v105, 0x3e38aa3b, v78
	v_mul_f32_e32 v106, 0x3e38aa3b, v79
	v_mul_f32_e32 v107, 0x3e38aa3b, v68
	v_mul_f32_e32 v108, 0x3e38aa3b, v69
	v_mul_f32_e32 v109, 0x3e38aa3b, v70
	v_mul_f32_e32 v110, 0x3e38aa3b, v71
	v_mul_f32_e32 v111, 0x3e38aa3b, v44
	v_mul_f32_e32 v112, 0x3e38aa3b, v45
	v_mul_f32_e32 v113, 0x3e38aa3b, v46
	v_mul_f32_e32 v114, 0x3e38aa3b, v47
	v_ashrrev_i32_e32 v3, 31, v2
	v_lshlrev_b64 v[44:45], 7, v[2:3]
	v_lshl_add_u64 v[44:45], v[142:143], 0, v[44:45]
	global_load_dwordx4 v[88:91], v[44:45], off
	global_load_dwordx4 v[84:87], v[44:45], off offset:1024
	global_load_dwordx4 v[80:83], v[44:45], off offset:2048
	global_load_dwordx4 v[76:79], v[44:45], off offset:3072
	v_add_co_u32_e32 v44, vcc, s33, v44
	s_nop 1
	v_addc_co_u32_e32 v45, vcc, 0, v45, vcc
	global_load_dwordx4 v[72:75], v[44:45], off
	global_load_dwordx4 v[68:71], v[44:45], off offset:1024
	global_load_dwordx4 v[52:55], v[44:45], off offset:2048
	s_nop 0
	global_load_dwordx4 v[44:47], v[44:45], off offset:3072
	v_max3_f32 v98, v99, s3, v100
	v_max3_f32 v98, v98, v101, v102
	v_max3_f32 v98, v98, v103, v104
	v_max3_f32 v98, v98, v105, v106
	v_max3_f32 v98, v98, v107, v108
	v_max3_f32 v98, v98, v109, v110
	v_max3_f32 v98, v98, v111, v112
	v_max3_f32 v98, v98, v113, v114
	v_mov_b32_e32 v115, v98
	s_nop 1
	v_permlane16_swap_b32_e32 v115, v98
	v_max_f32_e32 v98, v98, v115
	v_mov_b32_e32 v115, v98
	s_nop 1
	v_permlane32_swap_b32_e32 v115, v98
	v_max3_f32 v98, v92, v98, v115
	v_sub_f32_e32 v92, v92, v98
	v_exp_f32_e32 v92, v92
	s_nop 0
	v_cmp_neq_f32_e32 vcc, 1.0, v92
	s_cbranch_vccz .LBB0_102
	v_pk_mul_f32 v[26:27], v[26:27], v[92:93] op_sel_hi:[1,0]
	v_pk_mul_f32 v[24:25], v[24:25], v[92:93] op_sel_hi:[1,0]
	v_pk_mul_f32 v[22:23], v[22:23], v[92:93] op_sel_hi:[1,0]
	v_pk_mul_f32 v[20:21], v[20:21], v[92:93] op_sel_hi:[1,0]
	v_pk_mul_f32 v[18:19], v[18:19], v[92:93] op_sel_hi:[1,0]
	v_pk_mul_f32 v[16:17], v[16:17], v[92:93] op_sel_hi:[1,0]
	v_pk_mul_f32 v[14:15], v[14:15], v[92:93] op_sel_hi:[1,0]
	v_pk_mul_f32 v[12:13], v[12:13], v[92:93] op_sel_hi:[1,0]
	s_branch .LBB0_102
